# plus: mix3 GLU loop fully unrolled with all 16 W_glu fragments preloaded before the barrier (no global-load waits inside the MFMA loop)
# speedup vs baseline: 1.0093x; 1.0093x over previous
.LBB0_1614:
	v_readlane_b32 s7, v253, 51
	s_ashr_i32 s81, s80, 31
	v_mov_b32_e32 v43, v64
	v_or_b32_e32 v42, s7, v230
	v_or_b32_e32 v40, 16, v42
	v_mov_b32_e32 v41, v64
	s_lshl_b64 s[12:13], s[80:81], 17
	v_lshlrev_b64 v[0:1], 9, v[42:43]
	v_lshlrev_b64 v[2:3], 9, v[40:41]
	v_mul_u32_u24_e32 v4, 0x210, v230
	v_add3_u32 v41, v4, v231, 0
	v_lshl_add_u64 v[2:3], s[12:13], 0, v[2:3]
	v_lshlrev_b64 v[4:5], 1, v[110:111]
	v_lshl_add_u64 v[0:1], s[12:13], 0, v[0:1]
	v_lshl_add_u64 v[2:3], v[2:3], 0, v[4:5]
	v_lshl_add_u64 v[0:1], v[0:1], 0, v[4:5]
	v_mov_b32_e32 v65, v64
	v_lshl_add_u64 v[44:45], s[78:79], 0, v[2:3]
	v_lshl_add_u64 v[46:47], s[78:79], 0, v[0:1]
	global_load_dwordx4 v[76:79], v[46:47], off offset:-128
	global_load_dwordx4 v[80:83], v[44:45], off offset:-128
	global_load_dwordx4 v[84:87], v[46:47], off offset:-64
	global_load_dwordx4 v[88:91], v[44:45], off offset:-64
	global_load_dwordx4 v[92:95], v[46:47], off
	global_load_dwordx4 v[96:99], v[44:45], off
	global_load_dwordx4 v[100:103], v[46:47], off offset:64
	global_load_dwordx4 v[112:115], v[44:45], off offset:64
	global_load_dwordx4 v[116:119], v[46:47], off offset:128
	global_load_dwordx4 v[120:123], v[44:45], off offset:128
	global_load_dwordx4 v[124:127], v[46:47], off offset:192
	global_load_dwordx4 v[128:131], v[44:45], off offset:192
	global_load_dwordx4 v[132:135], v[46:47], off offset:256
	global_load_dwordx4 v[136:139], v[44:45], off offset:256
	global_load_dwordx4 v[140:143], v[46:47], off offset:320
	global_load_dwordx4 v[144:147], v[44:45], off offset:320
	v_mov_b32_e32 v66, v64
	v_mov_b32_e32 v67, v64
	v_mov_b32_e32 v16, 0
	v_mov_b64_e32 v[0:1], v[64:65]
	v_mov_b64_e32 v[12:13], v[64:65]
	v_mov_b64_e32 v[4:5], v[64:65]
	v_mov_b64_e32 v[20:21], v[64:65]
	v_mov_b64_e32 v[8:9], v[64:65]
	v_mov_b64_e32 v[24:25], v[64:65]
	s_movk_i32 s7, 0xfe00
	v_mov_b64_e32 v[2:3], v[66:67]
	v_mov_b64_e32 v[14:15], v[66:67]
	v_mov_b64_e32 v[6:7], v[66:67]
	v_mov_b64_e32 v[22:23], v[66:67]
	v_mov_b64_e32 v[10:11], v[66:67]
	v_mov_b64_e32 v[26:27], v[66:67]
	v_mov_b32_e32 v17, v16
	v_mov_b32_e32 v18, v16
	v_mov_b32_e32 v19, v16
	v_mov_b32_e32 v28, v16
	v_mov_b32_e32 v29, v16
	v_mov_b32_e32 v30, v16
	v_mov_b32_e32 v31, v16
	v_readlane_b32 s84, v252, 23
	v_readlane_b32 s81, v252, 20
	s_waitcnt lgkmcnt(0)
	s_barrier
	s_waitcnt vmcnt(0)
.Lglu0_1616:
	v_add_u32_e32 v43, s7, v41
	v_add_u32_e32 v48, 0x15200, v43
	ds_read_b128 v[48:51], v48
	v_cndmask_b32_e64 v52, 0, 1, s[38:39]
	v_cmp_ne_u32_e64 s[40:41], 1, v52
	s_andn2_b64 vcc, exec, s[38:39]
	s_waitcnt lgkmcnt(0)
	v_mfma_f32_16x16x32_bf16 v[28:31], v[48:51], v[76:79], v[28:31]
	v_mfma_f32_16x16x32_bf16 v[16:19], v[48:51], v[80:83], v[16:19]
	s_cbranch_vccnz .Lglu0_1631
	v_add_u32_e32 v48, 0x17300, v43
	ds_read_b128 v[48:51], v48
	s_waitcnt lgkmcnt(0)
	v_mfma_f32_16x16x32_bf16 v[24:27], v[48:51], v[76:79], v[24:27]
	v_mfma_f32_16x16x32_bf16 v[8:11], v[48:51], v[80:83], v[8:11]
	s_and_b64 vcc, exec, s[40:41]
	s_cbranch_vccz .Lglu0_1632

.Lglu0_1619:
	v_add_u32_e32 v48, 0x1b500, v43
	ds_read_b128 v[48:51], v48
	s_waitcnt lgkmcnt(0)
	v_mfma_f32_16x16x32_bf16 v[12:15], v[48:51], v[76:79], v[12:15]
	v_mfma_f32_16x16x32_bf16 v[0:3], v[48:51], v[80:83], v[0:3]
.Lglu0_1620:
	v_add_u32_e32 v36, 0x15240, v43
	ds_read_b128 v[48:51], v36
	s_and_b64 vcc, exec, s[40:41]
	s_waitcnt lgkmcnt(0)
	v_mfma_f32_16x16x32_bf16 v[28:31], v[48:51], v[84:87], v[28:31]
	v_mfma_f32_16x16x32_bf16 v[16:19], v[48:51], v[88:91], v[16:19]
	s_cbranch_vccnz .Lglu0_1633
	v_add_u32_e32 v48, 0x17340, v43
	ds_read_b128 v[48:51], v48
	s_waitcnt lgkmcnt(0)
	v_mfma_f32_16x16x32_bf16 v[24:27], v[48:51], v[84:87], v[24:27]
	v_mfma_f32_16x16x32_bf16 v[8:11], v[48:51], v[88:91], v[8:11]
	s_and_b64 vcc, exec, s[40:41]
	s_cbranch_vccz .Lglu0_1634

.Lglu0_1623:
	v_add_u32_e32 v48, 0x1b540, v43
	ds_read_b128 v[48:51], v48
	s_waitcnt lgkmcnt(0)
	v_mfma_f32_16x16x32_bf16 v[12:15], v[48:51], v[84:87], v[12:15]
	v_mfma_f32_16x16x32_bf16 v[0:3], v[48:51], v[88:91], v[0:3]
.Lglu0_1624:
	v_add_u32_e32 v36, 0x15280, v43
	ds_read_b128 v[48:51], v36
	s_and_b64 vcc, exec, s[40:41]
	s_waitcnt lgkmcnt(0)
	v_mfma_f32_16x16x32_bf16 v[28:31], v[48:51], v[92:95], v[28:31]
	v_mfma_f32_16x16x32_bf16 v[16:19], v[48:51], v[96:99], v[16:19]
	s_cbranch_vccnz .Lglu0_1635
	v_add_u32_e32 v48, 0x17380, v43
	ds_read_b128 v[48:51], v48
	s_waitcnt lgkmcnt(0)
	v_mfma_f32_16x16x32_bf16 v[24:27], v[48:51], v[92:95], v[24:27]
	v_mfma_f32_16x16x32_bf16 v[8:11], v[48:51], v[96:99], v[8:11]
	s_and_b64 vcc, exec, s[40:41]
	s_cbranch_vccz .Lglu0_1636

.Lglu0_1627:
	v_add_u32_e32 v48, 0x1b580, v43
	ds_read_b128 v[48:51], v48
	s_waitcnt lgkmcnt(0)
	v_mfma_f32_16x16x32_bf16 v[12:15], v[48:51], v[92:95], v[12:15]
	v_mfma_f32_16x16x32_bf16 v[0:3], v[48:51], v[96:99], v[0:3]
.Lglu0_1628:
	v_add_u32_e32 v36, 0x152c0, v43
	ds_read_b128 v[48:51], v36
	s_and_b64 vcc, exec, s[40:41]
	s_waitcnt lgkmcnt(0)
	v_mfma_f32_16x16x32_bf16 v[28:31], v[48:51], v[100:103], v[28:31]
	v_mfma_f32_16x16x32_bf16 v[16:19], v[48:51], v[112:115], v[16:19]
	s_cbranch_vccnz .Lglu0_1637
	v_add_u32_e32 v48, 0x173c0, v43
	ds_read_b128 v[48:51], v48
	s_waitcnt lgkmcnt(0)
	v_mfma_f32_16x16x32_bf16 v[24:27], v[48:51], v[100:103], v[24:27]
	v_mfma_f32_16x16x32_bf16 v[8:11], v[48:51], v[112:115], v[8:11]
	s_and_b64 vcc, exec, s[40:41]
	s_cbranch_vccz .Lglu0_1638

.Lglu0_1632:
	v_add_u32_e32 v48, 0x19400, v43
	ds_read_b128 v[48:51], v48
	s_waitcnt lgkmcnt(0)
	v_mfma_f32_16x16x32_bf16 v[20:23], v[48:51], v[76:79], v[20:23]
	v_mfma_f32_16x16x32_bf16 v[4:7], v[48:51], v[80:83], v[4:7]
	s_and_b64 vcc, exec, s[40:41]
	s_cbranch_vccz .Lglu0_1619
	s_branch .Lglu0_1620

.Lglu0_1634:
	v_add_u32_e32 v48, 0x19440, v43
	ds_read_b128 v[48:51], v48
	s_waitcnt lgkmcnt(0)
	v_mfma_f32_16x16x32_bf16 v[20:23], v[48:51], v[84:87], v[20:23]
	v_mfma_f32_16x16x32_bf16 v[4:7], v[48:51], v[88:91], v[4:7]
	s_and_b64 vcc, exec, s[40:41]
	s_cbranch_vccz .Lglu0_1623
	s_branch .Lglu0_1624

.Lglu0_1636:
	v_add_u32_e32 v48, 0x19480, v43
	ds_read_b128 v[48:51], v48
	s_waitcnt lgkmcnt(0)
	v_mfma_f32_16x16x32_bf16 v[20:23], v[48:51], v[92:95], v[20:23]
	v_mfma_f32_16x16x32_bf16 v[4:7], v[48:51], v[96:99], v[4:7]
	s_and_b64 vcc, exec, s[40:41]
	s_cbranch_vccz .Lglu0_1627
	s_branch .Lglu0_1628

.Lglu0_1638:
	v_add_u32_e32 v48, 0x194c0, v43
	ds_read_b128 v[48:51], v48
	s_waitcnt lgkmcnt(0)
	v_mfma_f32_16x16x32_bf16 v[20:23], v[48:51], v[100:103], v[20:23]
	v_mfma_f32_16x16x32_bf16 v[4:7], v[48:51], v[112:115], v[4:7]
	s_and_b64 vcc, exec, s[40:41]
	s_cbranch_vccnz .Lglu_next
.Lglu0_1639:
	v_add_u32_e32 v43, 0x1b5c0, v43
	ds_read_b128 v[48:51], v43
	s_waitcnt lgkmcnt(0)
	v_mfma_f32_16x16x32_bf16 v[12:15], v[48:51], v[100:103], v[12:15]
	v_mfma_f32_16x16x32_bf16 v[0:3], v[48:51], v[112:115], v[0:3]
	s_branch .Lglu_next

.Lglu1_1616:
	v_add_u32_e32 v43, s7, v41
	v_add_u32_e32 v48, 0x15200, v43
	ds_read_b128 v[48:51], v48
	v_cndmask_b32_e64 v52, 0, 1, s[38:39]
	v_cmp_ne_u32_e64 s[40:41], 1, v52
	s_andn2_b64 vcc, exec, s[38:39]
	s_waitcnt lgkmcnt(0)
	v_mfma_f32_16x16x32_bf16 v[28:31], v[48:51], v[116:119], v[28:31]
	v_mfma_f32_16x16x32_bf16 v[16:19], v[48:51], v[120:123], v[16:19]
	s_cbranch_vccnz .Lglu1_1631
	v_add_u32_e32 v48, 0x17300, v43
	ds_read_b128 v[48:51], v48
	s_waitcnt lgkmcnt(0)
	v_mfma_f32_16x16x32_bf16 v[24:27], v[48:51], v[116:119], v[24:27]
	v_mfma_f32_16x16x32_bf16 v[8:11], v[48:51], v[120:123], v[8:11]
	s_and_b64 vcc, exec, s[40:41]
	s_cbranch_vccz .Lglu1_1632

.Lglu1_1619:
	v_add_u32_e32 v48, 0x1b500, v43
	ds_read_b128 v[48:51], v48
	s_waitcnt lgkmcnt(0)
	v_mfma_f32_16x16x32_bf16 v[12:15], v[48:51], v[116:119], v[12:15]
	v_mfma_f32_16x16x32_bf16 v[0:3], v[48:51], v[120:123], v[0:3]
.Lglu1_1620:
	v_add_u32_e32 v36, 0x15240, v43
	ds_read_b128 v[48:51], v36
	s_and_b64 vcc, exec, s[40:41]
	s_waitcnt lgkmcnt(0)
	v_mfma_f32_16x16x32_bf16 v[28:31], v[48:51], v[124:127], v[28:31]
	v_mfma_f32_16x16x32_bf16 v[16:19], v[48:51], v[128:131], v[16:19]
	s_cbranch_vccnz .Lglu1_1633
	v_add_u32_e32 v48, 0x17340, v43
	ds_read_b128 v[48:51], v48
	s_waitcnt lgkmcnt(0)
	v_mfma_f32_16x16x32_bf16 v[24:27], v[48:51], v[124:127], v[24:27]
	v_mfma_f32_16x16x32_bf16 v[8:11], v[48:51], v[128:131], v[8:11]
	s_and_b64 vcc, exec, s[40:41]
	s_cbranch_vccz .Lglu1_1634

.Lglu1_1623:
	v_add_u32_e32 v48, 0x1b540, v43
	ds_read_b128 v[48:51], v48
	s_waitcnt lgkmcnt(0)
	v_mfma_f32_16x16x32_bf16 v[12:15], v[48:51], v[124:127], v[12:15]
	v_mfma_f32_16x16x32_bf16 v[0:3], v[48:51], v[128:131], v[0:3]
.Lglu1_1624:
	v_add_u32_e32 v36, 0x15280, v43
	ds_read_b128 v[48:51], v36
	s_and_b64 vcc, exec, s[40:41]
	s_waitcnt lgkmcnt(0)
	v_mfma_f32_16x16x32_bf16 v[28:31], v[48:51], v[132:135], v[28:31]
	v_mfma_f32_16x16x32_bf16 v[16:19], v[48:51], v[136:139], v[16:19]
	s_cbranch_vccnz .Lglu1_1635
	v_add_u32_e32 v48, 0x17380, v43
	ds_read_b128 v[48:51], v48
	s_waitcnt lgkmcnt(0)
	v_mfma_f32_16x16x32_bf16 v[24:27], v[48:51], v[132:135], v[24:27]
	v_mfma_f32_16x16x32_bf16 v[8:11], v[48:51], v[136:139], v[8:11]
	s_and_b64 vcc, exec, s[40:41]
	s_cbranch_vccz .Lglu1_1636

.Lglu1_1627:
	v_add_u32_e32 v48, 0x1b580, v43
	ds_read_b128 v[48:51], v48
	s_waitcnt lgkmcnt(0)
	v_mfma_f32_16x16x32_bf16 v[12:15], v[48:51], v[132:135], v[12:15]
	v_mfma_f32_16x16x32_bf16 v[0:3], v[48:51], v[136:139], v[0:3]
.Lglu1_1628:
	v_add_u32_e32 v36, 0x152c0, v43
	ds_read_b128 v[48:51], v36
	s_and_b64 vcc, exec, s[40:41]
	s_waitcnt lgkmcnt(0)
	v_mfma_f32_16x16x32_bf16 v[28:31], v[48:51], v[140:143], v[28:31]
	v_mfma_f32_16x16x32_bf16 v[16:19], v[48:51], v[144:147], v[16:19]
	s_cbranch_vccnz .Lglu1_1637
	v_add_u32_e32 v48, 0x173c0, v43
	ds_read_b128 v[48:51], v48
	s_waitcnt lgkmcnt(0)
	v_mfma_f32_16x16x32_bf16 v[24:27], v[48:51], v[140:143], v[24:27]
	v_mfma_f32_16x16x32_bf16 v[8:11], v[48:51], v[144:147], v[8:11]
	s_and_b64 vcc, exec, s[40:41]
	s_cbranch_vccz .Lglu1_1638

.Lglu1_1632:
	v_add_u32_e32 v48, 0x19400, v43
	ds_read_b128 v[48:51], v48
	s_waitcnt lgkmcnt(0)
	v_mfma_f32_16x16x32_bf16 v[20:23], v[48:51], v[116:119], v[20:23]
	v_mfma_f32_16x16x32_bf16 v[4:7], v[48:51], v[120:123], v[4:7]
	s_and_b64 vcc, exec, s[40:41]
	s_cbranch_vccz .Lglu1_1619
	s_branch .Lglu1_1620

.Lglu1_1634:
	v_add_u32_e32 v48, 0x19440, v43
	ds_read_b128 v[48:51], v48
	s_waitcnt lgkmcnt(0)
	v_mfma_f32_16x16x32_bf16 v[20:23], v[48:51], v[124:127], v[20:23]
	v_mfma_f32_16x16x32_bf16 v[4:7], v[48:51], v[128:131], v[4:7]
	s_and_b64 vcc, exec, s[40:41]
	s_cbranch_vccz .Lglu1_1623
	s_branch .Lglu1_1624

.Lglu1_1636:
	v_add_u32_e32 v48, 0x19480, v43
	ds_read_b128 v[48:51], v48
	s_waitcnt lgkmcnt(0)
	v_mfma_f32_16x16x32_bf16 v[20:23], v[48:51], v[132:135], v[20:23]
	v_mfma_f32_16x16x32_bf16 v[4:7], v[48:51], v[136:139], v[4:7]
	s_and_b64 vcc, exec, s[40:41]
	s_cbranch_vccz .Lglu1_1627
	s_branch .Lglu1_1628

.Lglu1_1638:
	v_add_u32_e32 v48, 0x194c0, v43
	ds_read_b128 v[48:51], v48
	s_waitcnt lgkmcnt(0)
	v_mfma_f32_16x16x32_bf16 v[20:23], v[48:51], v[140:143], v[20:23]
	v_mfma_f32_16x16x32_bf16 v[4:7], v[48:51], v[144:147], v[4:7]
	s_and_b64 vcc, exec, s[40:41]
	s_cbranch_vccnz .LBB0_1640
.Lglu1_1639:
	v_add_u32_e32 v43, 0x1b5c0, v43
	ds_read_b128 v[48:51], v43
	s_waitcnt lgkmcnt(0)
	v_mfma_f32_16x16x32_bf16 v[12:15], v[48:51], v[140:143], v[12:15]
	v_mfma_f32_16x16x32_bf16 v[0:3], v[48:51], v[144:147], v[0:3]
	s_branch .LBB0_1640
